# small latency trims: DIL unit end waits LDS only; XCC-id check loads batched; scan preamble lambda loads beside log_dt
# speedup vs baseline: 1.0210x; 1.0020x over previous
; __device__ __forceinline__ int tid_here(int wave) { int z = 0; asm volatile("" : "+v"(z)); return wave * 64 + (int)__builtin_amdgcn_mbcnt_hi(~0u, __builtin_amdgcn_mbcnt_lo(~0u, (unsigned)z)); }
; __device__ __forceinline__ unsigned xb_ld(unsigned* p)              { return __hip_atomic_load(p, __ATOMIC_RELAXED, __HIP_MEMORY_SCOPE_AGENT); }
; __device__ __forceinline__ unsigned xb_add(unsigned* p, unsigned v) { return __hip_atomic_fetch_add(p, v, __ATOMIC_RELAXED, __HIP_MEMORY_SCOPE_AGENT); }
; #define LDP(i) ((unsigned char*)(GAS unsigned char*)(((unsigned long long)(unsigned)__builtin_amdgcn_readfirstlane((int)(LPv[i] >> 32)) << 32) | (unsigned long long)(unsigned)__builtin_amdgcn_readfirstlane((int)(unsigned)LPv[i])))
; __global__ void __launch_bounds__(NWAVES * 64, 2) mk_fwd(Args a) {
;     ...
;         else if (!first) { for (int rp = 0; rp < REP_GRID; ++rp) { XcdBarrier b2 = bar; b2.bar = (unsigned*)(LDP(28) + WS_CTL) + CW_BAR; xcd_barrier(b2); }
;             if (G == 256 && li == 0 && sub == 1 && tid_here(wave0) == 0) { unsigned* bw = (unsigned*)(LDP(28) + WS_CTL) + CW_BAR; const unsigned me = xb_ld(&bw[XB_XCCID + bx]); bool loc = true;
;                 for (int q = 0; q < 4; ++q) loc = loc && (xb_ld(&bw[XB_XCCID + (bx & 63) + 64 * q]) == me);
;                 if (loc) (void)xb_add(&bw[XB_NLOCAL], 1u); }
.LBB0_121:
	s_or_b64 exec, exec, s[12:13]
	v_readlane_b32 s12, v252, 2
	v_readlane_b32 s13, v252, 3
	s_cmp_lt_u32 s12, 16
	v_readlane_b32 s14, v252, 4
	s_cselect_b64 s[12:13], -1, 0
	v_readlane_b32 s15, v252, 5
	s_and_b64 s[12:13], s[14:15], s[12:13]
	s_and_b64 s[2:3], s[12:13], s[2:3]
	s_andn2_b64 vcc, exec, s[2:3]
	s_waitcnt lgkmcnt(0)
	s_barrier
	s_cbranch_vccnz .LBB0_130
	v_mov_b32_e32 v0, v209
	v_readlane_b32 s2, v252, 40
	v_mbcnt_lo_u32_b32 v0, -1, v0
	v_mbcnt_hi_u32_b32 v0, -1, v0
	v_cmp_eq_u32_e32 vcc, s2, v0
	s_and_saveexec_b64 s[2:3], vcc
	s_cbranch_execz .LBB0_129
	ds_read_b64 v[0:1], v236 offset:224
	ds_read_b64 v[2:3], v236 offset:224
	s_mov_b32 s14, s97
	v_readlane_b32 s16, v252, 63
	v_readlane_b32 s17, v253, 0
	s_waitcnt lgkmcnt(0)
	v_readfirstlane_b32 s15, v1
	s_waitcnt lgkmcnt(0)
	v_readfirstlane_b32 s96, v2
	s_or_b64 s[14:15], s[96:97], s[14:15]
	s_add_u32 s5, s14, 0x4000
	s_addc_u32 s18, s15, 0
	s_lshl_b64 s[16:17], s[16:17], 2
	s_add_u32 s16, s5, s16
	s_addc_u32 s17, s18, s17
	v_mov_b32_e32 v1, 0x3000
	global_load_dword v0, v1, s[16:17] offset:1536 sc1
	v_readlane_b32 s16, v254, 4
	s_add_u32 s16, s5, s16
	s_addc_u32 s17, s18, 0
	v_mov_b32_e32 v2, 0x3000
	s_nop 1
	global_load_dword v1, v1, s[16:17] offset:1536 sc1
	global_load_dword v3, v2, s[16:17] offset:1792 sc1
	global_load_dword v4, v2, s[16:17] offset:2048 sc1
	global_load_dword v5, v2, s[16:17] offset:2304 sc1
	s_waitcnt vmcnt(0)
	v_cmp_ne_u32_e32 vcc, v1, v0
	s_cbranch_vccnz .LBB0_129
	v_cmp_ne_u32_e32 vcc, v3, v0
	s_cbranch_vccnz .LBB0_129
	v_cmp_ne_u32_e32 vcc, v4, v0
	s_cbranch_vccnz .LBB0_129
	v_cmp_ne_u32_e32 vcc, v5, v0
	s_cbranch_vccnz .LBB0_129
	s_mov_b64 s[16:17], exec
	v_mbcnt_lo_u32_b32 v0, s16, 0
	v_mbcnt_hi_u32_b32 v0, s17, v0
	v_cmp_eq_u32_e32 vcc, 0, v0
	s_and_b64 s[18:19], exec, vcc
	s_mov_b64 exec, s[18:19]
	s_cbranch_execz .LBB0_129
	s_bcnt1_i32_b64 s5, s[16:17]
	v_mov_b32_e32 v0, s5
	global_atomic_add v230, v0, s[14:15] offset:1408

; #define ATT_SYNC() do { asm volatile("s_waitcnt vmcnt(0) lgkmcnt(0)" ::: "memory"); __syncthreads(); } while (0)
; __device__ __forceinline__ void dil_unit(LAS unsigned char* lds, const LAS float* btab, const bf16_t* QKV, int gi, int ldil, int b, int h, int r, int ub, bf16_t* AO, float* lseacc, const int tid) {
;     ...
;     if (hi == 0) *lp = ln;
;     ATT_SYNC();
; __global__ void __launch_bounds__(NWAVES * 64, 2) mk_fwd(Args a) {
;     ...
;             for (int u = vcu; u < 512; u += G) { const int x = u & 15, bh = u >> 4, h = bh & 7;
;                 int tu = tid; asm volatile("" : "+v"(tu));
;                 if (tu < 192) { const int jk = tu - 32; btab[tu] = (jk >= 0 && jk <= 128) ? biasrel[(gi * 8 + h) * 129 + jk] : -1e30f; }
;                 att::dil_unit(lds, btab, (const bf16_t*)BIG, gi, ldil, bh >> 3, h, x & ((1 << ldil) - 1), x >> ldil, T1, (float*)(wsb + WS_MISC + 65536), tu); }
.LBB0_657:
	s_or_b64 exec, exec, s[0:1]
	s_waitcnt lgkmcnt(0)
	v_readlane_b32 s0, v253, 63
	s_add_i32 s19, s19, s0
	s_cmpk_gt_i32 s19, 0x1ff
	s_barrier
	v_readlane_b32 s1, v254, 0
	s_cbranch_scc1 .LBB0_689

; __device__ __forceinline__ void s5_scan_bg(LAS unsigned char* lds, const S5In P, const bf16_t* F, bf16_t* XB, int b, int g, const int tid) {
;     ...
;     for (int di = 0; di < 2; ++di) { const int gp = (di * 64 + g) * 64 + p;
;         const float dt = expf(P.log_dt[di * 64 + g]); const float lr = P.lam_re[gp], li = P.lam_im[gp];
;         const float mag = expf(lr * dt), ang = li * dt; float ar = mag * cosf(ang), ai = mag * sinf(ang);
.LBB0_802:
	v_writelane_b32 v254, s6, 52
	s_ashr_i32 s75, s74, 31
	s_lshl_b64 s[0:1], s[74:75], 2
	v_writelane_b32 v254, s7, 53
	v_lshl_or_b32 v4, s74, 6, v108
	v_readlane_b32 s2, v254, 45
	s_add_u32 s0, s2, s0
	v_readlane_b32 s2, v254, 46
	s_addc_u32 s1, s2, s1
	global_load_dword v8, v209, s[0:1]
	v_ashrrev_i32_e32 v5, 31, v4
	v_readlane_b32 s2, v254, 43
	v_lshlrev_b64 v[4:5], 2, v[4:5]
	v_readlane_b32 s3, v254, 44
	s_nop 1
	v_lshl_add_u64 v[6:7], s[2:3], 0, v[4:5]
	global_load_dword v9, v[6:7], off
	v_readlane_b32 s2, v254, 41
	v_readlane_b32 s3, v254, 42
	s_nop 1
	v_lshl_add_u64 v[4:5], s[2:3], 0, v[4:5]
	global_load_dword v6, v[4:5], off
	s_waitcnt vmcnt(2)
	v_cmp_ngt_f32_e32 vcc, s92, v8
	v_mul_f32_e32 v4, 0x3fb8aa3b, v8
	v_fma_f32 v5, v8, s89, -v4
	v_rndne_f32_e32 v7, v4
	v_fmac_f32_e32 v5, 0x32a5705f, v8
	v_sub_f32_e32 v4, v4, v7
	v_add_f32_e32 v4, v4, v5
	v_cvt_i32_f32_e32 v7, v7
	v_exp_f32_e32 v4, v4
	s_brev_b32 s2, 18
	v_ldexp_f32 v4, v4, v7
	v_cndmask_b32_e32 v4, 0, v4, vcc
	v_cmp_nlt_f32_e32 vcc, s93, v8
	s_nop 1
	v_cndmask_b32_e32 v7, v232, v4, vcc
	s_waitcnt vmcnt(1)
	v_mul_f32_e32 v4, v7, v9
	v_and_b32_e32 v5, 0x7fffffff, v4
	v_lshrrev_b32_e32 v8, 23, v5
	v_and_b32_e32 v9, 0x7fffff, v5
	v_cmp_nlt_f32_e64 s[2:3], |v4|, s2
	v_add_u32_e32 v13, 0xffffff88, v8
	v_or_b32_e32 v12, 0x800000, v9
	s_and_saveexec_b64 s[4:5], s[2:3]
	s_xor_b64 s[4:5], exec, s[4:5]
	s_cbranch_execz .LBB0_804
	v_cmp_lt_u32_e32 vcc, 63, v13
	s_mov_b32 s6, 0xfe5163ab
	s_nop 0
	v_cndmask_b32_e32 v8, 0, v233, vcc
	v_add_u32_e32 v8, v8, v13
	v_cmp_lt_u32_e64 s[42:43], 31, v8
	s_nop 1
	v_cndmask_b32_e64 v9, 0, v234, s[42:43]
	v_add_u32_e32 v8, v9, v8
	v_cmp_lt_u32_e64 s[44:45], 31, v8
	s_nop 1
	v_cndmask_b32_e64 v9, 0, v234, s[44:45]
	v_add_u32_e32 v24, v9, v8
	v_mad_u64_u32 v[8:9], s[6:7], v12, s6, 0
	v_mov_b32_e32 v208, v9
	s_mov_b32 s6, 0x3c439041
	v_mad_u64_u32 v[10:11], s[6:7], v12, s6, v[208:209]
	v_mov_b32_e32 v208, v11
	s_mov_b32 s6, 0xdb629599
	v_mad_u64_u32 v[14:15], s[6:7], v12, s6, v[208:209]
	v_mov_b32_e32 v208, v15
	s_mov_b32 s6, 0xf534ddc0
	v_mad_u64_u32 v[16:17], s[6:7], v12, s6, v[208:209]
	v_mov_b32_e32 v208, v17
	s_mov_b32 s6, 0xfc2757d1
	v_mad_u64_u32 v[18:19], s[6:7], v12, s6, v[208:209]
	v_mov_b32_e32 v208, v19
	s_mov_b32 s6, 0x4e441529
	v_mad_u64_u32 v[20:21], s[6:7], v12, s6, v[208:209]
	v_mov_b32_e32 v208, v21
	s_mov_b32 s6, 0xa2f9836e
	v_mad_u64_u32 v[22:23], s[6:7], v12, s6, v[208:209]
	v_cndmask_b32_e32 v9, v20, v16, vcc
	v_cndmask_b32_e32 v11, v22, v18, vcc
	v_cndmask_b32_e32 v17, v23, v20, vcc
	v_cndmask_b32_e64 v15, v11, v9, s[42:43]
	v_cndmask_b32_e64 v11, v17, v11, s[42:43]
	v_cndmask_b32_e32 v17, v18, v14, vcc
	v_cndmask_b32_e64 v9, v9, v17, s[42:43]
	v_cndmask_b32_e32 v10, v16, v10, vcc
	v_cndmask_b32_e64 v11, v11, v15, s[44:45]
	v_cndmask_b32_e64 v15, v15, v9, s[44:45]
	v_sub_u32_e32 v18, 32, v24
	v_cndmask_b32_e64 v16, v17, v10, s[42:43]
	v_alignbit_b32 v19, v11, v15, v18
	v_cmp_eq_u32_e64 s[46:47], 0, v24
	v_cndmask_b32_e64 v9, v9, v16, s[44:45]
	v_alignbit_b32 v17, v15, v9, v18
	v_cndmask_b32_e64 v11, v19, v11, s[46:47]
	v_cndmask_b32_e32 v8, v14, v8, vcc
	v_cndmask_b32_e64 v15, v17, v15, s[46:47]
	v_bfe_u32 v20, v11, 29, 1
	v_cndmask_b32_e64 v8, v10, v8, s[42:43]
	v_alignbit_b32 v17, v11, v15, 30
	v_sub_u32_e32 v21, 0, v20
	v_cndmask_b32_e64 v8, v16, v8, s[44:45]
	v_xor_b32_e32 v17, v17, v21
	v_alignbit_b32 v10, v9, v8, v18
	v_cndmask_b32_e64 v9, v10, v9, s[46:47]
	v_ffbh_u32_e32 v14, v17
	v_alignbit_b32 v10, v15, v9, 30
	v_min_u32_e32 v14, 32, v14
	v_alignbit_b32 v8, v9, v8, 30
	v_xor_b32_e32 v10, v10, v21
	v_sub_u32_e32 v15, 31, v14
	v_xor_b32_e32 v8, v8, v21
	v_alignbit_b32 v16, v17, v10, v15
	v_alignbit_b32 v8, v10, v8, v15
	v_alignbit_b32 v9, v16, v8, 9
	v_ffbh_u32_e32 v10, v9
	v_min_u32_e32 v10, 32, v10
	v_lshrrev_b32_e32 v19, 29, v11
	v_not_b32_e32 v15, v10
	v_alignbit_b32 v8, v9, v8, v15
	v_lshlrev_b32_e32 v9, 31, v19
	v_or_b32_e32 v15, 0x33000000, v9
	v_add_lshl_u32 v10, v10, v14, 23
	v_lshrrev_b32_e32 v8, 9, v8
	v_sub_u32_e32 v10, v15, v10
	v_or_b32_e32 v9, 0.5, v9
	v_lshlrev_b32_e32 v14, 23, v14
	v_or_b32_e32 v8, v10, v8
	v_lshrrev_b32_e32 v10, 9, v16
	v_sub_u32_e32 v9, v9, v14
	v_or_b32_e32 v9, v10, v9
	v_mul_f32_e32 v10, 0x3fc90fda, v9
	s_mov_b32 s6, 0x3fc90fda
	v_fma_f32 v14, v9, s6, -v10
	v_fmac_f32_e32 v14, 0x33a22168, v9
	v_fmac_f32_e32 v14, 0x3fc90fda, v8
	v_lshrrev_b32_e32 v8, 30, v11
	v_add_f32_e32 v9, v10, v14
	v_add_u32_e32 v8, v20, v8

; __device__ __forceinline__ void s5_scan_bg(LAS unsigned char* lds, const S5In P, const bf16_t* F, bf16_t* XB, int b, int g, const int tid) {
;     ...
;     for (int di = 0; di < 2; ++di) { const int gp = (di * 64 + g) * 64 + p;
;         const float dt = expf(P.log_dt[di * 64 + g]); const float lr = P.lam_re[gp], li = P.lam_im[gp];
;         const float mag = expf(lr * dt), ang = li * dt; float ar = mag * cosf(ang), ai = mag * sinf(ang);
.LBB0_810:
	s_or_b64 exec, exec, s[2:3]
	global_load_dword v16, v209, s[0:1] offset:256
	s_lshl_b32 s0, s74, 6
	s_addk_i32 s0, 0x1000
	v_or_b32_e32 v12, s0, v108
	v_ashrrev_i32_e32 v13, 31, v12
	v_readlane_b32 s0, v254, 43
	v_lshlrev_b64 v[12:13], 2, v[12:13]
	v_readlane_b32 s1, v254, 44
	s_nop 1
	v_lshl_add_u64 v[14:15], s[0:1], 0, v[12:13]
	global_load_dword v14, v[14:15], off
	v_readlane_b32 s0, v254, 41
	v_readlane_b32 s1, v254, 42
	s_nop 1
	v_lshl_add_u64 v[12:13], s[0:1], 0, v[12:13]
	global_load_dword v18, v[12:13], off
	s_waitcnt vmcnt(2)
	v_cmp_ngt_f32_e32 vcc, s92, v16
	v_mul_f32_e32 v12, 0x3fb8aa3b, v16
	v_fma_f32 v13, v16, s89, -v12
	v_rndne_f32_e32 v15, v12
	v_fmac_f32_e32 v13, 0x32a5705f, v16
	v_sub_f32_e32 v12, v12, v15
	v_add_f32_e32 v12, v12, v13
	v_cvt_i32_f32_e32 v15, v15
	v_exp_f32_e32 v12, v12
	s_brev_b32 s0, 18
	v_ldexp_f32 v12, v12, v15
	v_cndmask_b32_e32 v12, 0, v12, vcc
	v_cmp_nlt_f32_e32 vcc, s93, v16
	s_nop 1
	v_cndmask_b32_e32 v19, v232, v12, vcc
	s_waitcnt vmcnt(1)
	v_mul_f32_e32 v12, v19, v14
	v_and_b32_e32 v13, 0x7fffffff, v12
	v_lshrrev_b32_e32 v14, 23, v13
	v_and_b32_e32 v15, 0x7fffff, v13
	v_cmp_nlt_f32_e64 s[0:1], |v12|, s0
	v_add_u32_e32 v21, 0xffffff88, v14
	v_or_b32_e32 v20, 0x800000, v15
	s_and_saveexec_b64 s[2:3], s[0:1]
	s_xor_b64 s[2:3], exec, s[2:3]
	s_cbranch_execz .LBB0_812
	v_cmp_lt_u32_e32 vcc, 63, v21
	s_mov_b32 s4, 0xfe5163ab
	s_nop 0
	v_cndmask_b32_e32 v14, 0, v233, vcc
	v_add_u32_e32 v14, v14, v21
	v_cmp_lt_u32_e64 s[42:43], 31, v14
	s_nop 1
	v_cndmask_b32_e64 v15, 0, v234, s[42:43]
	v_add_u32_e32 v14, v15, v14
	v_cmp_lt_u32_e64 s[44:45], 31, v14
	s_nop 1
	v_cndmask_b32_e64 v15, 0, v234, s[44:45]
	v_add_u32_e32 v32, v15, v14
	v_mad_u64_u32 v[14:15], s[4:5], v20, s4, 0
	v_mov_b32_e32 v208, v15
	s_mov_b32 s4, 0x3c439041
	v_mad_u64_u32 v[16:17], s[4:5], v20, s4, v[208:209]
	v_mov_b32_e32 v208, v17
	s_mov_b32 s4, 0xdb629599
	v_mad_u64_u32 v[22:23], s[4:5], v20, s4, v[208:209]
	v_mov_b32_e32 v208, v23
	s_mov_b32 s4, 0xf534ddc0
	v_mad_u64_u32 v[24:25], s[4:5], v20, s4, v[208:209]
	v_mov_b32_e32 v208, v25
	s_mov_b32 s4, 0xfc2757d1
	v_mad_u64_u32 v[26:27], s[4:5], v20, s4, v[208:209]
	v_mov_b32_e32 v208, v27
	s_mov_b32 s4, 0x4e441529
	v_mad_u64_u32 v[28:29], s[4:5], v20, s4, v[208:209]
	v_mov_b32_e32 v208, v29
	s_mov_b32 s4, 0xa2f9836e
	v_mad_u64_u32 v[30:31], s[4:5], v20, s4, v[208:209]
	v_cndmask_b32_e32 v15, v28, v24, vcc
	v_cndmask_b32_e32 v17, v30, v26, vcc
	v_cndmask_b32_e32 v25, v31, v28, vcc
	v_cndmask_b32_e64 v23, v17, v15, s[42:43]
	v_cndmask_b32_e64 v17, v25, v17, s[42:43]
	v_cndmask_b32_e32 v25, v26, v22, vcc
	v_cndmask_b32_e64 v15, v15, v25, s[42:43]
	v_cndmask_b32_e32 v16, v24, v16, vcc
	v_cndmask_b32_e64 v17, v17, v23, s[44:45]
	v_cndmask_b32_e64 v23, v23, v15, s[44:45]
	v_sub_u32_e32 v26, 32, v32
	v_cndmask_b32_e64 v24, v25, v16, s[42:43]
	v_alignbit_b32 v27, v17, v23, v26
	v_cmp_eq_u32_e64 s[46:47], 0, v32
	v_cndmask_b32_e64 v15, v15, v24, s[44:45]
	v_alignbit_b32 v25, v23, v15, v26
	v_cndmask_b32_e64 v17, v27, v17, s[46:47]
	v_cndmask_b32_e32 v14, v22, v14, vcc
	v_cndmask_b32_e64 v23, v25, v23, s[46:47]
	v_bfe_u32 v28, v17, 29, 1
	v_cndmask_b32_e64 v14, v16, v14, s[42:43]
	v_alignbit_b32 v25, v17, v23, 30
	v_sub_u32_e32 v29, 0, v28
	v_cndmask_b32_e64 v14, v24, v14, s[44:45]
	v_xor_b32_e32 v25, v25, v29
	v_alignbit_b32 v16, v15, v14, v26
	v_cndmask_b32_e64 v15, v16, v15, s[46:47]
	v_ffbh_u32_e32 v22, v25
	v_alignbit_b32 v16, v23, v15, 30
	v_min_u32_e32 v22, 32, v22
	v_alignbit_b32 v14, v15, v14, 30
	v_xor_b32_e32 v16, v16, v29
	v_sub_u32_e32 v23, 31, v22
	v_xor_b32_e32 v14, v14, v29
	v_alignbit_b32 v24, v25, v16, v23
	v_alignbit_b32 v14, v16, v14, v23
	v_alignbit_b32 v15, v24, v14, 9
	v_ffbh_u32_e32 v16, v15
	v_min_u32_e32 v16, 32, v16
	v_lshrrev_b32_e32 v27, 29, v17
	v_not_b32_e32 v23, v16
	v_alignbit_b32 v14, v15, v14, v23
	v_lshlrev_b32_e32 v15, 31, v27
	v_or_b32_e32 v23, 0x33000000, v15
	v_add_lshl_u32 v16, v16, v22, 23
	v_lshrrev_b32_e32 v14, 9, v14
	v_sub_u32_e32 v16, v23, v16
	v_or_b32_e32 v15, 0.5, v15
	v_lshlrev_b32_e32 v22, 23, v22
	v_or_b32_e32 v14, v16, v14
	v_lshrrev_b32_e32 v16, 9, v24
	v_sub_u32_e32 v15, v15, v22
	v_or_b32_e32 v15, v16, v15
	v_mul_f32_e32 v16, 0x3fc90fda, v15
	s_mov_b32 s4, 0x3fc90fda
	v_fma_f32 v22, v15, s4, -v16
	v_fmac_f32_e32 v22, 0x33a22168, v15
	v_fmac_f32_e32 v22, 0x3fc90fda, v14
	v_lshrrev_b32_e32 v14, 30, v17
	v_add_f32_e32 v15, v16, v22
	v_add_u32_e32 v14, v28, v14
